# LDS-DMA C loop with a single tile-end barrier instead of the double barrier
# baseline (speedup 1.0000x reference)
; DI float ex2(float x) { return __builtin_amdgcn_exp2f(x); }
; #define MFMA32(a, b, c) __builtin_amdgcn_mfma_f32_32x32x16_bf16((a), (b), (c), 0, 0, 0)
; template <int MODE>
; DI void attn_unit(unsigned char* lds, const AttnParams& ap, int b, int h, int qb, int tid) {
;     ...
;     for (int c = 0; c < NCH; ++c) { *(u32x4*)(Ks0 + (c * 64 + lrow) * 72 + 8 * lch) = kreg[c]; *(u32x4*)(Vs0 + (c * 64 + lrow) * 72 + 8 * lch) = vreg[c]; }
;     __syncthreads();
;     if (n + NCH < ntiles) {
; #pragma unroll
;       for (int c = 0; c < NCH; ++c) { const int jn = (MODE == 2) ? jb - NCH - c : jb + NCH + c; kreg[c] = *(const u32x4*)(kg + (size_t)jn * 64 * PLD); vreg[c] = *(const u32x4*)(vg + (size_t)jn * 4096); } }
; #pragma unroll
;     for (int c = 0; c < NCH; ++c) {
;     const int j = (MODE == 2) ? jb - c : jb + c;
;     const bf16_t* Ks = Ks0 + c * 64 * 72; const bf16_t* Vs = Vs0 + c * 64 * 72;
;     const bool active = (j <= cw) && (MODE != 0 || j >= cw - 8);
;     if (!active) continue;
;     if (MODE == 2 && D_EARLY && wdone) continue;
;     if (MODE == 1) {
; #pragma unroll
;       for (int kh = 0; kh < 2; ++kh) {
;         const bf16_t* kb = Ks + (32 * kh + r32) * 72 + 8 * hi;
;         bf16x8 p0[2], p1[2];
;         { f32x16 s0 = splat16(ap.negM);
;           s0 = MFMA32(*(const bf16x8*)(kb), qf[0], s0); s0 = MFMA32(*(const bf16x8*)(kb + 16), qf[1], s0);
; #pragma unroll
;           for (int i = 0; i < 16; ++i) { s0[i] = ex2(s0[i]); l0 += s0[i]; }
;           p0[0] = pack8(s0, 0); p0[1] = pack8(s0, 1); }
;         { f32x16 s1 = splat16(ap.negM);
;           s1 = MFMA32(*(const bf16x8*)(kb + 32), qf[2], s1); s1 = MFMA32(*(const bf16x8*)(kb + 48), qf[3], s1);
; #pragma unroll
;           for (int i = 0; i < 16; ++i) { s1[i] = ex2(s1[i]); l1 += s1[i]; }
;           p1[0] = pack8(s1, 0); p1[1] = pack8(s1, 1); }
; #pragma unroll
;         for (int kk = 0; kk < 2; ++kk) {
; #pragma unroll
;           for (int eb = 0; eb < 2; ++eb) { const bf16_t* vb = Vs + (32 * eb + r32) * 72 + 32 * kh + 16 * kk + 8 * hi; const bf16x8 vf = *(const bf16x8*)vb;
;             O0[eb] = MFMA32(vf, p0[kk], O0[eb]); O1[eb] = MFMA32(vf, p1[kk], O1[eb]); } }
.Lc_tile_ph0:
	s_add_i32 m0, s0, 32768
	s_nop 0
	global_load_lds_dwordx4 v32, s[2:3]
	s_add_i32 m0, s0, 40960
	s_nop 0
	global_load_lds_dwordx4 v157, s[10:11]
	s_add_u32 s2, s2, 0x68800
	s_addc_u32 s3, s3, 0
	s_add_u32 s10, s10, 0x2000
	s_addc_u32 s11, s11, 0
	s_waitcnt lgkmcnt(0)
	v_mfma_f32_32x32x16_bf16 v[116:131], v[166:169], v[38:41], v[48:63]
	v_exp_f32_e32 v96, v96
	v_exp_f32_e32 v97, v97
	v_exp_f32_e32 v98, v98
	v_exp_f32_e32 v99, v99
	v_mfma_f32_32x32x16_bf16 v[116:131], v[170:173], v[34:37], v[116:131]
	v_exp_f32_e32 v100, v100
	v_exp_f32_e32 v101, v101
	v_exp_f32_e32 v102, v102
	v_exp_f32_e32 v103, v103
	ds_read_b128 v[166:169], v146 offset:4096
	ds_read_b128 v[170:173], v147 offset:4096
	v_mfma_f32_32x32x16_bf16 v[80:95], v[174:177], v[158:161], v[80:95]
	v_exp_f32_e32 v104, v104
	v_exp_f32_e32 v105, v105
	v_add_f32_e32 v141, v141, v96
	v_add_f32_e32 v150, v150, v97
	v_add_f32_e32 v141, v141, v98
	v_add_f32_e32 v150, v150, v99
	v_mfma_f32_32x32x16_bf16 v[16:31], v[182:185], v[158:161], v[16:31]
	v_exp_f32_e32 v106, v106
	v_exp_f32_e32 v107, v107
	v_cvt_pk_bf16_f32 v158, v96, v97
	v_cvt_pk_bf16_f32 v159, v98, v99
	v_add_f32_e32 v141, v141, v100
	v_add_f32_e32 v150, v150, v101
	v_mfma_f32_32x32x16_bf16 v[80:95], v[178:181], v[162:165], v[80:95]
	v_exp_f32_e32 v108, v108
	v_exp_f32_e32 v109, v109
	v_cvt_pk_bf16_f32 v160, v100, v101
	v_cvt_pk_bf16_f32 v161, v102, v103
	v_add_f32_e32 v141, v141, v102
	v_add_f32_e32 v150, v150, v103
	v_mfma_f32_32x32x16_bf16 v[16:31], v[186:189], v[162:165], v[16:31]
	ds_read_b128 v[174:177], v146 offset:8192
	ds_read_b128 v[178:181], v147 offset:8192
	ds_read_b128 v[182:185], v146 offset:12288
	ds_read_b128 v[186:189], v147 offset:12288
	v_exp_f32_e32 v110, v110
	v_exp_f32_e32 v111, v111
	v_add_f32_e32 v141, v141, v104
	v_add_f32_e32 v150, v150, v105
	v_add_f32_e32 v141, v141, v106
	v_add_f32_e32 v150, v150, v107
	v_add_f32_e32 v141, v141, v108
	v_add_f32_e32 v150, v150, v109
	v_cvt_pk_bf16_f32 v162, v104, v105
	v_cvt_pk_bf16_f32 v163, v106, v107
	v_cvt_pk_bf16_f32 v164, v108, v109
	v_add_f32_e32 v141, v141, v110
	v_add_f32_e32 v150, v150, v111
	v_cvt_pk_bf16_f32 v165, v110, v111
	s_waitcnt lgkmcnt(0)
	v_mfma_f32_32x32x16_bf16 v[96:111], v[166:169], v[112:115], v[48:63]
	v_exp_f32_e32 v116, v116
	v_exp_f32_e32 v117, v117
	v_exp_f32_e32 v118, v118
	v_exp_f32_e32 v119, v119
	v_mfma_f32_32x32x16_bf16 v[96:111], v[170:173], v[42:45], v[96:111]
	v_exp_f32_e32 v120, v120
	v_exp_f32_e32 v121, v121
	v_exp_f32_e32 v122, v122
	v_exp_f32_e32 v123, v123
	ds_read_b128 v[166:169], v148 offset:4096
	ds_read_b128 v[170:173], v149 offset:4096
	v_mfma_f32_32x32x16_bf16 v[64:79], v[174:177], v[158:161], v[64:79]
	v_exp_f32_e32 v124, v124
	v_exp_f32_e32 v125, v125
	v_add_f32_e32 v140, v140, v116
	v_add_f32_e32 v151, v151, v117
	v_add_f32_e32 v140, v140, v118
	v_add_f32_e32 v151, v151, v119
	v_mfma_f32_32x32x16_bf16 v[0:15], v[182:185], v[158:161], v[0:15]
	v_exp_f32_e32 v126, v126
	v_exp_f32_e32 v127, v127
	v_cvt_pk_bf16_f32 v158, v116, v117
	v_cvt_pk_bf16_f32 v159, v118, v119
	v_add_f32_e32 v140, v140, v120
	v_add_f32_e32 v151, v151, v121
	v_mfma_f32_32x32x16_bf16 v[64:79], v[178:181], v[162:165], v[64:79]
	v_exp_f32_e32 v128, v128
	v_exp_f32_e32 v129, v129
	v_cvt_pk_bf16_f32 v160, v120, v121
	v_cvt_pk_bf16_f32 v161, v122, v123
	v_add_f32_e32 v140, v140, v122
	v_add_f32_e32 v151, v151, v123
	v_mfma_f32_32x32x16_bf16 v[0:15], v[186:189], v[162:165], v[0:15]
	v_exp_f32_e32 v130, v130
	v_exp_f32_e32 v131, v131
	v_add_f32_e32 v140, v140, v124
	v_add_f32_e32 v151, v151, v125
	v_add_f32_e32 v140, v140, v126
	v_add_f32_e32 v151, v151, v127
	v_add_f32_e32 v140, v140, v128
	v_add_f32_e32 v151, v151, v129
	v_cvt_pk_bf16_f32 v162, v124, v125
	v_cvt_pk_bf16_f32 v163, v126, v127
	v_cvt_pk_bf16_f32 v164, v128, v129
	v_add_f32_e32 v140, v140, v130
	v_add_f32_e32 v151, v151, v131
	v_cvt_pk_bf16_f32 v165, v130, v131
	s_waitcnt lgkmcnt(0)
	v_mfma_f32_32x32x16_bf16 v[116:131], v[166:169], v[38:41], v[48:63]
	v_exp_f32_e32 v96, v96
	v_exp_f32_e32 v97, v97
	v_exp_f32_e32 v98, v98
	v_exp_f32_e32 v99, v99
	v_mfma_f32_32x32x16_bf16 v[116:131], v[170:173], v[34:37], v[116:131]
	v_exp_f32_e32 v100, v100
	v_exp_f32_e32 v101, v101
	v_exp_f32_e32 v102, v102
	v_exp_f32_e32 v103, v103
	ds_read_b128 v[166:169], v146 offset:16384
	ds_read_b128 v[170:173], v147 offset:16384
	v_mfma_f32_32x32x16_bf16 v[80:95], v[174:177], v[158:161], v[80:95]
	v_exp_f32_e32 v104, v104
	v_exp_f32_e32 v105, v105
	v_add_f32_e32 v141, v141, v96
	v_add_f32_e32 v150, v150, v97
	v_add_f32_e32 v141, v141, v98
	v_add_f32_e32 v150, v150, v99
	v_mfma_f32_32x32x16_bf16 v[16:31], v[182:185], v[158:161], v[16:31]
	v_exp_f32_e32 v106, v106
	v_exp_f32_e32 v107, v107
	v_cvt_pk_bf16_f32 v158, v96, v97
	v_cvt_pk_bf16_f32 v159, v98, v99
	v_add_f32_e32 v141, v141, v100
	v_add_f32_e32 v150, v150, v101
	v_mfma_f32_32x32x16_bf16 v[80:95], v[178:181], v[162:165], v[80:95]
	v_exp_f32_e32 v108, v108
	v_exp_f32_e32 v109, v109
	v_cvt_pk_bf16_f32 v160, v100, v101
	v_cvt_pk_bf16_f32 v161, v102, v103
	v_add_f32_e32 v141, v141, v102
	v_add_f32_e32 v150, v150, v103
	v_mfma_f32_32x32x16_bf16 v[16:31], v[186:189], v[162:165], v[16:31]
	ds_read_b128 v[174:177], v148 offset:8192
	ds_read_b128 v[178:181], v149 offset:8192
	ds_read_b128 v[182:185], v148 offset:12288
	ds_read_b128 v[186:189], v149 offset:12288
	v_exp_f32_e32 v110, v110
	v_exp_f32_e32 v111, v111
	v_add_f32_e32 v141, v141, v104
	v_add_f32_e32 v150, v150, v105
	v_add_f32_e32 v141, v141, v106
	v_add_f32_e32 v150, v150, v107
	v_add_f32_e32 v141, v141, v108
	v_add_f32_e32 v150, v150, v109
	v_cvt_pk_bf16_f32 v162, v104, v105
	v_cvt_pk_bf16_f32 v163, v106, v107
	v_cvt_pk_bf16_f32 v164, v108, v109
	v_add_f32_e32 v141, v141, v110
	v_add_f32_e32 v150, v150, v111
	v_cvt_pk_bf16_f32 v165, v110, v111
	s_waitcnt lgkmcnt(0)
; DI float ex2(float x) { return __builtin_amdgcn_exp2f(x); }
; #define MFMA32(a, b, c) __builtin_amdgcn_mfma_f32_32x32x16_bf16((a), (b), (c), 0, 0, 0)
; template <int MODE>
; DI void attn_unit(unsigned char* lds, const AttnParams& ap, int b, int h, int qb, int tid) {
;     ...
;     for (int c = 0; c < NCH; ++c) { *(u32x4*)(Ks0 + (c * 64 + lrow) * 72 + 8 * lch) = kreg[c]; *(u32x4*)(Vs0 + (c * 64 + lrow) * 72 + 8 * lch) = vreg[c]; }
;     __syncthreads();
;     if (n + NCH < ntiles) {
; #pragma unroll
;       for (int c = 0; c < NCH; ++c) { const int jn = (MODE == 2) ? jb - NCH - c : jb + NCH + c; kreg[c] = *(const u32x4*)(kg + (size_t)jn * 64 * PLD); vreg[c] = *(const u32x4*)(vg + (size_t)jn * 4096); } }
; #pragma unroll
;     for (int c = 0; c < NCH; ++c) {
;     const int j = (MODE == 2) ? jb - c : jb + c;
;     const bf16_t* Ks = Ks0 + c * 64 * 72; const bf16_t* Vs = Vs0 + c * 64 * 72;
;     const bool active = (j <= cw) && (MODE != 0 || j >= cw - 8);
;     if (!active) continue;
;     if (MODE == 2 && D_EARLY && wdone) continue;
;     if (MODE == 1) {
; #pragma unroll
;       for (int kh = 0; kh < 2; ++kh) {
;         const bf16_t* kb = Ks + (32 * kh + r32) * 72 + 8 * hi;
;         bf16x8 p0[2], p1[2];
;         { f32x16 s0 = splat16(ap.negM);
;           s0 = MFMA32(*(const bf16x8*)(kb), qf[0], s0); s0 = MFMA32(*(const bf16x8*)(kb + 16), qf[1], s0);
; #pragma unroll
;           for (int i = 0; i < 16; ++i) { s0[i] = ex2(s0[i]); l0 += s0[i]; }
;           p0[0] = pack8(s0, 0); p0[1] = pack8(s0, 1); }
;         { f32x16 s1 = splat16(ap.negM);
;           s1 = MFMA32(*(const bf16x8*)(kb + 32), qf[2], s1); s1 = MFMA32(*(const bf16x8*)(kb + 48), qf[3], s1);
; #pragma unroll
;           for (int i = 0; i < 16; ++i) { s1[i] = ex2(s1[i]); l1 += s1[i]; }
;           p1[0] = pack8(s1, 0); p1[1] = pack8(s1, 1); }
; #pragma unroll
;         for (int kk = 0; kk < 2; ++kk) {
; #pragma unroll
;           for (int eb = 0; eb < 2; ++eb) { const bf16_t* vb = Vs + (32 * eb + r32) * 72 + 32 * kh + 16 * kk + 8 * hi; const bf16x8 vf = *(const bf16x8*)vb;
;             O0[eb] = MFMA32(vf, p0[kk], O0[eb]); O1[eb] = MFMA32(vf, p1[kk], O1[eb]); } }
	v_mfma_f32_32x32x16_bf16 v[96:111], v[166:169], v[112:115], v[48:63]
	v_exp_f32_e32 v116, v116
	v_exp_f32_e32 v117, v117
	v_exp_f32_e32 v118, v118
	v_exp_f32_e32 v119, v119
	v_mfma_f32_32x32x16_bf16 v[96:111], v[170:173], v[42:45], v[96:111]
	v_exp_f32_e32 v120, v120
	v_exp_f32_e32 v121, v121
	v_exp_f32_e32 v122, v122
	v_exp_f32_e32 v123, v123
	ds_read_b128 v[166:169], v148 offset:16384
	ds_read_b128 v[170:173], v149 offset:16384
	v_mfma_f32_32x32x16_bf16 v[64:79], v[174:177], v[158:161], v[64:79]
	v_exp_f32_e32 v124, v124
	v_exp_f32_e32 v125, v125
	v_add_f32_e32 v140, v140, v116
	v_add_f32_e32 v151, v151, v117
	v_add_f32_e32 v140, v140, v118
	v_add_f32_e32 v151, v151, v119
	v_mfma_f32_32x32x16_bf16 v[0:15], v[182:185], v[158:161], v[0:15]
	v_exp_f32_e32 v126, v126
	v_exp_f32_e32 v127, v127
	v_cvt_pk_bf16_f32 v158, v116, v117
	v_cvt_pk_bf16_f32 v159, v118, v119
	v_add_f32_e32 v140, v140, v120
	v_add_f32_e32 v151, v151, v121
	v_mfma_f32_32x32x16_bf16 v[64:79], v[178:181], v[162:165], v[64:79]
	v_exp_f32_e32 v128, v128
	v_exp_f32_e32 v129, v129
	v_cvt_pk_bf16_f32 v160, v120, v121
	v_cvt_pk_bf16_f32 v161, v122, v123
	v_add_f32_e32 v140, v140, v122
	v_add_f32_e32 v151, v151, v123
	v_mfma_f32_32x32x16_bf16 v[0:15], v[186:189], v[162:165], v[0:15]
	v_exp_f32_e32 v130, v130
	v_exp_f32_e32 v131, v131
	v_add_f32_e32 v140, v140, v124
	v_add_f32_e32 v151, v151, v125
	v_add_f32_e32 v140, v140, v126
	v_add_f32_e32 v151, v151, v127
	v_add_f32_e32 v140, v140, v128
	v_add_f32_e32 v151, v151, v129
	v_cvt_pk_bf16_f32 v162, v124, v125
	v_cvt_pk_bf16_f32 v163, v126, v127
	v_cvt_pk_bf16_f32 v164, v128, v129
	v_add_f32_e32 v140, v140, v130
	v_add_f32_e32 v151, v151, v131
	v_cvt_pk_bf16_f32 v165, v130, v131
	s_add_i32 s4, s4, 1
	s_waitcnt vmcnt(0) lgkmcnt(0)
	s_barrier
	s_cmp_le_u32 s4, s5
	s_cbranch_scc1 .Lc_tile_ph1
	s_mov_b32 s9, 1
	s_branch .Lc_drain
.Lc_tile_ph1:
	s_add_i32 m0, s0, 0
	s_nop 0
	global_load_lds_dwordx4 v32, s[2:3]
	s_add_i32 m0, s0, 8192
	s_nop 0
	global_load_lds_dwordx4 v157, s[10:11]
	s_add_u32 s2, s2, 0x68800
	s_addc_u32 s3, s3, 0
	s_add_u32 s10, s10, 0x2000
	s_addc_u32 s11, s11, 0
	s_waitcnt lgkmcnt(0)
	v_mfma_f32_32x32x16_bf16 v[116:131], v[166:169], v[38:41], v[48:63]
	v_exp_f32_e32 v96, v96
	v_exp_f32_e32 v97, v97
	v_exp_f32_e32 v98, v98
	v_exp_f32_e32 v99, v99
	v_mfma_f32_32x32x16_bf16 v[116:131], v[170:173], v[34:37], v[116:131]
	v_exp_f32_e32 v100, v100
	v_exp_f32_e32 v101, v101
	v_exp_f32_e32 v102, v102
	v_exp_f32_e32 v103, v103
	ds_read_b128 v[166:169], v146 offset:20480
	ds_read_b128 v[170:173], v147 offset:20480
	v_mfma_f32_32x32x16_bf16 v[80:95], v[174:177], v[158:161], v[80:95]
	v_exp_f32_e32 v104, v104
	v_exp_f32_e32 v105, v105
	v_add_f32_e32 v141, v141, v96
	v_add_f32_e32 v150, v150, v97
	v_add_f32_e32 v141, v141, v98
	v_add_f32_e32 v150, v150, v99
	v_mfma_f32_32x32x16_bf16 v[16:31], v[182:185], v[158:161], v[16:31]
	v_exp_f32_e32 v106, v106
	v_exp_f32_e32 v107, v107
	v_cvt_pk_bf16_f32 v158, v96, v97
	v_cvt_pk_bf16_f32 v159, v98, v99
	v_add_f32_e32 v141, v141, v100
	v_add_f32_e32 v150, v150, v101
	v_mfma_f32_32x32x16_bf16 v[80:95], v[178:181], v[162:165], v[80:95]
	v_exp_f32_e32 v108, v108
	v_exp_f32_e32 v109, v109
	v_cvt_pk_bf16_f32 v160, v100, v101
	v_cvt_pk_bf16_f32 v161, v102, v103
	v_add_f32_e32 v141, v141, v102
	v_add_f32_e32 v150, v150, v103
	v_mfma_f32_32x32x16_bf16 v[16:31], v[186:189], v[162:165], v[16:31]
	ds_read_b128 v[174:177], v146 offset:24576
	ds_read_b128 v[178:181], v147 offset:24576
	ds_read_b128 v[182:185], v146 offset:28672
	ds_read_b128 v[186:189], v147 offset:28672
	v_exp_f32_e32 v110, v110
	v_exp_f32_e32 v111, v111
	v_add_f32_e32 v141, v141, v104
	v_add_f32_e32 v150, v150, v105
	v_add_f32_e32 v141, v141, v106
	v_add_f32_e32 v150, v150, v107
	v_add_f32_e32 v141, v141, v108
	v_add_f32_e32 v150, v150, v109
	v_cvt_pk_bf16_f32 v162, v104, v105
	v_cvt_pk_bf16_f32 v163, v106, v107
	v_cvt_pk_bf16_f32 v164, v108, v109
	v_add_f32_e32 v141, v141, v110
	v_add_f32_e32 v150, v150, v111
	v_cvt_pk_bf16_f32 v165, v110, v111
	s_waitcnt lgkmcnt(0)
	v_mfma_f32_32x32x16_bf16 v[96:111], v[166:169], v[112:115], v[48:63]
	v_exp_f32_e32 v116, v116
	v_exp_f32_e32 v117, v117
	v_exp_f32_e32 v118, v118
	v_exp_f32_e32 v119, v119
	v_mfma_f32_32x32x16_bf16 v[96:111], v[170:173], v[42:45], v[96:111]
	v_exp_f32_e32 v120, v120
	v_exp_f32_e32 v121, v121
	v_exp_f32_e32 v122, v122
	v_exp_f32_e32 v123, v123
	ds_read_b128 v[166:169], v148 offset:20480
	ds_read_b128 v[170:173], v149 offset:20480
	v_mfma_f32_32x32x16_bf16 v[64:79], v[174:177], v[158:161], v[64:79]
	v_exp_f32_e32 v124, v124
	v_exp_f32_e32 v125, v125
	v_add_f32_e32 v140, v140, v116
	v_add_f32_e32 v151, v151, v117
	v_add_f32_e32 v140, v140, v118
	v_add_f32_e32 v151, v151, v119
	v_mfma_f32_32x32x16_bf16 v[0:15], v[182:185], v[158:161], v[0:15]
	v_exp_f32_e32 v126, v126
	v_exp_f32_e32 v127, v127
	v_cvt_pk_bf16_f32 v158, v116, v117
	v_cvt_pk_bf16_f32 v159, v118, v119
	v_add_f32_e32 v140, v140, v120
	v_add_f32_e32 v151, v151, v121
	v_mfma_f32_32x32x16_bf16 v[64:79], v[178:181], v[162:165], v[64:79]
	v_exp_f32_e32 v128, v128
	v_exp_f32_e32 v129, v129
	v_cvt_pk_bf16_f32 v160, v120, v121
	v_cvt_pk_bf16_f32 v161, v122, v123
	v_add_f32_e32 v140, v140, v122
	v_add_f32_e32 v151, v151, v123
	v_mfma_f32_32x32x16_bf16 v[0:15], v[186:189], v[162:165], v[0:15]
	v_exp_f32_e32 v130, v130
	v_exp_f32_e32 v131, v131
	v_add_f32_e32 v140, v140, v124
	v_add_f32_e32 v151, v151, v125
	v_add_f32_e32 v140, v140, v126
	v_add_f32_e32 v151, v151, v127
	v_add_f32_e32 v140, v140, v128
	v_add_f32_e32 v151, v151, v129
	v_cvt_pk_bf16_f32 v162, v124, v125
	v_cvt_pk_bf16_f32 v163, v126, v127
	v_cvt_pk_bf16_f32 v164, v128, v129
	v_add_f32_e32 v140, v140, v130
	v_add_f32_e32 v151, v151, v131
	v_cvt_pk_bf16_f32 v165, v130, v131
	s_waitcnt lgkmcnt(0)
; DI float ex2(float x) { return __builtin_amdgcn_exp2f(x); }
; #define MFMA32(a, b, c) __builtin_amdgcn_mfma_f32_32x32x16_bf16((a), (b), (c), 0, 0, 0)
; template <int MODE>
; DI void attn_unit(unsigned char* lds, const AttnParams& ap, int b, int h, int qb, int tid) {
;     ...
;     for (int c = 0; c < NCH; ++c) { *(u32x4*)(Ks0 + (c * 64 + lrow) * 72 + 8 * lch) = kreg[c]; *(u32x4*)(Vs0 + (c * 64 + lrow) * 72 + 8 * lch) = vreg[c]; }
;     __syncthreads();
;     if (n + NCH < ntiles) {
; #pragma unroll
;       for (int c = 0; c < NCH; ++c) { const int jn = (MODE == 2) ? jb - NCH - c : jb + NCH + c; kreg[c] = *(const u32x4*)(kg + (size_t)jn * 64 * PLD); vreg[c] = *(const u32x4*)(vg + (size_t)jn * 4096); } }
; #pragma unroll
;     for (int c = 0; c < NCH; ++c) {
;     const int j = (MODE == 2) ? jb - c : jb + c;
;     const bf16_t* Ks = Ks0 + c * 64 * 72; const bf16_t* Vs = Vs0 + c * 64 * 72;
;     const bool active = (j <= cw) && (MODE != 0 || j >= cw - 8);
;     if (!active) continue;
;     if (MODE == 2 && D_EARLY && wdone) continue;
;     if (MODE == 1) {
; #pragma unroll
;       for (int kh = 0; kh < 2; ++kh) {
;         const bf16_t* kb = Ks + (32 * kh + r32) * 72 + 8 * hi;
;         bf16x8 p0[2], p1[2];
;         { f32x16 s0 = splat16(ap.negM);
;           s0 = MFMA32(*(const bf16x8*)(kb), qf[0], s0); s0 = MFMA32(*(const bf16x8*)(kb + 16), qf[1], s0);
; #pragma unroll
;           for (int i = 0; i < 16; ++i) { s0[i] = ex2(s0[i]); l0 += s0[i]; }
;           p0[0] = pack8(s0, 0); p0[1] = pack8(s0, 1); }
;         { f32x16 s1 = splat16(ap.negM);
;           s1 = MFMA32(*(const bf16x8*)(kb + 32), qf[2], s1); s1 = MFMA32(*(const bf16x8*)(kb + 48), qf[3], s1);
; #pragma unroll
;           for (int i = 0; i < 16; ++i) { s1[i] = ex2(s1[i]); l1 += s1[i]; }
;           p1[0] = pack8(s1, 0); p1[1] = pack8(s1, 1); }
; #pragma unroll
;         for (int kk = 0; kk < 2; ++kk) {
; #pragma unroll
;           for (int eb = 0; eb < 2; ++eb) { const bf16_t* vb = Vs + (32 * eb + r32) * 72 + 32 * kh + 16 * kk + 8 * hi; const bf16x8 vf = *(const bf16x8*)vb;
;             O0[eb] = MFMA32(vf, p0[kk], O0[eb]); O1[eb] = MFMA32(vf, p1[kk], O1[eb]); } }
	v_mfma_f32_32x32x16_bf16 v[116:131], v[166:169], v[38:41], v[48:63]
	v_exp_f32_e32 v96, v96
	v_exp_f32_e32 v97, v97
	v_exp_f32_e32 v98, v98
	v_exp_f32_e32 v99, v99
	v_mfma_f32_32x32x16_bf16 v[116:131], v[170:173], v[34:37], v[116:131]
	v_exp_f32_e32 v100, v100
	v_exp_f32_e32 v101, v101
	v_exp_f32_e32 v102, v102
	v_exp_f32_e32 v103, v103
	ds_read_b128 v[166:169], v146 offset:32768
	ds_read_b128 v[170:173], v147 offset:32768
	v_mfma_f32_32x32x16_bf16 v[80:95], v[174:177], v[158:161], v[80:95]
	v_exp_f32_e32 v104, v104
	v_exp_f32_e32 v105, v105
	v_add_f32_e32 v141, v141, v96
	v_add_f32_e32 v150, v150, v97
	v_add_f32_e32 v141, v141, v98
	v_add_f32_e32 v150, v150, v99
	v_mfma_f32_32x32x16_bf16 v[16:31], v[182:185], v[158:161], v[16:31]
	v_exp_f32_e32 v106, v106
	v_exp_f32_e32 v107, v107
	v_cvt_pk_bf16_f32 v158, v96, v97
	v_cvt_pk_bf16_f32 v159, v98, v99
	v_add_f32_e32 v141, v141, v100
	v_add_f32_e32 v150, v150, v101
	v_mfma_f32_32x32x16_bf16 v[80:95], v[178:181], v[162:165], v[80:95]
	v_exp_f32_e32 v108, v108
	v_exp_f32_e32 v109, v109
	v_cvt_pk_bf16_f32 v160, v100, v101
	v_cvt_pk_bf16_f32 v161, v102, v103
	v_add_f32_e32 v141, v141, v102
	v_add_f32_e32 v150, v150, v103
	v_mfma_f32_32x32x16_bf16 v[16:31], v[186:189], v[162:165], v[16:31]
	ds_read_b128 v[174:177], v148 offset:24576
	ds_read_b128 v[178:181], v149 offset:24576
	ds_read_b128 v[182:185], v148 offset:28672
	ds_read_b128 v[186:189], v149 offset:28672
	v_exp_f32_e32 v110, v110
	v_exp_f32_e32 v111, v111
	v_add_f32_e32 v141, v141, v104
	v_add_f32_e32 v150, v150, v105
	v_add_f32_e32 v141, v141, v106
	v_add_f32_e32 v150, v150, v107
	v_add_f32_e32 v141, v141, v108
	v_add_f32_e32 v150, v150, v109
	v_cvt_pk_bf16_f32 v162, v104, v105
	v_cvt_pk_bf16_f32 v163, v106, v107
	v_cvt_pk_bf16_f32 v164, v108, v109
	v_add_f32_e32 v141, v141, v110
	v_add_f32_e32 v150, v150, v111
	v_cvt_pk_bf16_f32 v165, v110, v111
	s_waitcnt lgkmcnt(0)
	v_mfma_f32_32x32x16_bf16 v[96:111], v[166:169], v[112:115], v[48:63]
	v_exp_f32_e32 v116, v116
	v_exp_f32_e32 v117, v117
	v_exp_f32_e32 v118, v118
	v_exp_f32_e32 v119, v119
	v_mfma_f32_32x32x16_bf16 v[96:111], v[170:173], v[42:45], v[96:111]
	v_exp_f32_e32 v120, v120
	v_exp_f32_e32 v121, v121
	v_exp_f32_e32 v122, v122
	v_exp_f32_e32 v123, v123
	ds_read_b128 v[166:169], v148 offset:32768
	ds_read_b128 v[170:173], v149 offset:32768
	v_mfma_f32_32x32x16_bf16 v[64:79], v[174:177], v[158:161], v[64:79]
	v_exp_f32_e32 v124, v124
	v_exp_f32_e32 v125, v125
	v_add_f32_e32 v140, v140, v116
	v_add_f32_e32 v151, v151, v117
	v_add_f32_e32 v140, v140, v118
	v_add_f32_e32 v151, v151, v119
	v_mfma_f32_32x32x16_bf16 v[0:15], v[182:185], v[158:161], v[0:15]
	v_exp_f32_e32 v126, v126
	v_exp_f32_e32 v127, v127
	v_cvt_pk_bf16_f32 v158, v116, v117
	v_cvt_pk_bf16_f32 v159, v118, v119
	v_add_f32_e32 v140, v140, v120
	v_add_f32_e32 v151, v151, v121
	v_mfma_f32_32x32x16_bf16 v[64:79], v[178:181], v[162:165], v[64:79]
	v_exp_f32_e32 v128, v128
	v_exp_f32_e32 v129, v129
	v_cvt_pk_bf16_f32 v160, v120, v121
	v_cvt_pk_bf16_f32 v161, v122, v123
	v_add_f32_e32 v140, v140, v122
	v_add_f32_e32 v151, v151, v123
	v_mfma_f32_32x32x16_bf16 v[0:15], v[186:189], v[162:165], v[0:15]
	v_exp_f32_e32 v130, v130
	v_exp_f32_e32 v131, v131
	v_add_f32_e32 v140, v140, v124
	v_add_f32_e32 v151, v151, v125
	v_add_f32_e32 v140, v140, v126
	v_add_f32_e32 v151, v151, v127
	v_add_f32_e32 v140, v140, v128
	v_add_f32_e32 v151, v151, v129
	v_cvt_pk_bf16_f32 v162, v124, v125
	v_cvt_pk_bf16_f32 v163, v126, v127
	v_cvt_pk_bf16_f32 v164, v128, v129
	v_add_f32_e32 v140, v140, v130
	v_add_f32_e32 v151, v151, v131
	v_cvt_pk_bf16_f32 v165, v130, v131
	s_add_i32 s4, s4, 1
	s_waitcnt vmcnt(0) lgkmcnt(0)
	s_barrier
	s_cmp_le_u32 s4, s5
	s_cbranch_scc1 .Lc_tile_ph2
	s_mov_b32 s9, 2
	s_branch .Lc_drain
.Lc_tile_ph2:
	s_add_i32 m0, s0, 16384
	s_nop 0
	global_load_lds_dwordx4 v32, s[2:3]
	s_add_i32 m0, s0, 24576
	s_nop 0
	global_load_lds_dwordx4 v157, s[10:11]
	s_add_u32 s2, s2, 0x68800
	s_addc_u32 s3, s3, 0
	s_add_u32 s10, s10, 0x2000
	s_addc_u32 s11, s11, 0
	s_waitcnt lgkmcnt(0)
	v_mfma_f32_32x32x16_bf16 v[116:131], v[166:169], v[38:41], v[48:63]
	v_exp_f32_e32 v96, v96
	v_exp_f32_e32 v97, v97
	v_exp_f32_e32 v98, v98
	v_exp_f32_e32 v99, v99
	v_mfma_f32_32x32x16_bf16 v[116:131], v[170:173], v[34:37], v[116:131]
	v_exp_f32_e32 v100, v100
	v_exp_f32_e32 v101, v101
	v_exp_f32_e32 v102, v102
	v_exp_f32_e32 v103, v103
	ds_read_b128 v[166:169], v146 offset:36864
	ds_read_b128 v[170:173], v147 offset:36864
	v_mfma_f32_32x32x16_bf16 v[80:95], v[174:177], v[158:161], v[80:95]
	v_exp_f32_e32 v104, v104
	v_exp_f32_e32 v105, v105
	v_add_f32_e32 v141, v141, v96
	v_add_f32_e32 v150, v150, v97
	v_add_f32_e32 v141, v141, v98
	v_add_f32_e32 v150, v150, v99
	v_mfma_f32_32x32x16_bf16 v[16:31], v[182:185], v[158:161], v[16:31]
	v_exp_f32_e32 v106, v106
	v_exp_f32_e32 v107, v107
	v_cvt_pk_bf16_f32 v158, v96, v97
	v_cvt_pk_bf16_f32 v159, v98, v99
	v_add_f32_e32 v141, v141, v100
	v_add_f32_e32 v150, v150, v101
	v_mfma_f32_32x32x16_bf16 v[80:95], v[178:181], v[162:165], v[80:95]
	v_exp_f32_e32 v108, v108
	v_exp_f32_e32 v109, v109
	v_cvt_pk_bf16_f32 v160, v100, v101
	v_cvt_pk_bf16_f32 v161, v102, v103
	v_add_f32_e32 v141, v141, v102
	v_add_f32_e32 v150, v150, v103
	v_mfma_f32_32x32x16_bf16 v[16:31], v[186:189], v[162:165], v[16:31]
	ds_read_b128 v[174:177], v146 offset:40960
	ds_read_b128 v[178:181], v147 offset:40960
	ds_read_b128 v[182:185], v146 offset:45056
	ds_read_b128 v[186:189], v147 offset:45056
	v_exp_f32_e32 v110, v110
	v_exp_f32_e32 v111, v111
	v_add_f32_e32 v141, v141, v104
	v_add_f32_e32 v150, v150, v105
	v_add_f32_e32 v141, v141, v106
	v_add_f32_e32 v150, v150, v107
	v_add_f32_e32 v141, v141, v108
	v_add_f32_e32 v150, v150, v109
	v_cvt_pk_bf16_f32 v162, v104, v105
	v_cvt_pk_bf16_f32 v163, v106, v107
	v_cvt_pk_bf16_f32 v164, v108, v109
	v_add_f32_e32 v141, v141, v110
	v_add_f32_e32 v150, v150, v111
	v_cvt_pk_bf16_f32 v165, v110, v111
	s_waitcnt lgkmcnt(0)
; DI float ex2(float x) { return __builtin_amdgcn_exp2f(x); }
; #define MFMA32(a, b, c) __builtin_amdgcn_mfma_f32_32x32x16_bf16((a), (b), (c), 0, 0, 0)
; template <int MODE>
; DI void attn_unit(unsigned char* lds, const AttnParams& ap, int b, int h, int qb, int tid) {
;     ...
;     for (int c = 0; c < NCH; ++c) { *(u32x4*)(Ks0 + (c * 64 + lrow) * 72 + 8 * lch) = kreg[c]; *(u32x4*)(Vs0 + (c * 64 + lrow) * 72 + 8 * lch) = vreg[c]; }
;     __syncthreads();
;     if (n + NCH < ntiles) {
; #pragma unroll
;       for (int c = 0; c < NCH; ++c) { const int jn = (MODE == 2) ? jb - NCH - c : jb + NCH + c; kreg[c] = *(const u32x4*)(kg + (size_t)jn * 64 * PLD); vreg[c] = *(const u32x4*)(vg + (size_t)jn * 4096); } }
; #pragma unroll
;     for (int c = 0; c < NCH; ++c) {
;     const int j = (MODE == 2) ? jb - c : jb + c;
;     const bf16_t* Ks = Ks0 + c * 64 * 72; const bf16_t* Vs = Vs0 + c * 64 * 72;
;     const bool active = (j <= cw) && (MODE != 0 || j >= cw - 8);
;     if (!active) continue;
;     if (MODE == 2 && D_EARLY && wdone) continue;
;     if (MODE == 1) {
; #pragma unroll
;       for (int kh = 0; kh < 2; ++kh) {
;         const bf16_t* kb = Ks + (32 * kh + r32) * 72 + 8 * hi;
;         bf16x8 p0[2], p1[2];
;         { f32x16 s0 = splat16(ap.negM);
;           s0 = MFMA32(*(const bf16x8*)(kb), qf[0], s0); s0 = MFMA32(*(const bf16x8*)(kb + 16), qf[1], s0);
; #pragma unroll
;           for (int i = 0; i < 16; ++i) { s0[i] = ex2(s0[i]); l0 += s0[i]; }
;           p0[0] = pack8(s0, 0); p0[1] = pack8(s0, 1); }
;         { f32x16 s1 = splat16(ap.negM);
;           s1 = MFMA32(*(const bf16x8*)(kb + 32), qf[2], s1); s1 = MFMA32(*(const bf16x8*)(kb + 48), qf[3], s1);
; #pragma unroll
;           for (int i = 0; i < 16; ++i) { s1[i] = ex2(s1[i]); l1 += s1[i]; }
;           p1[0] = pack8(s1, 0); p1[1] = pack8(s1, 1); }
; #pragma unroll
;         for (int kk = 0; kk < 2; ++kk) {
; #pragma unroll
;           for (int eb = 0; eb < 2; ++eb) { const bf16_t* vb = Vs + (32 * eb + r32) * 72 + 32 * kh + 16 * kk + 8 * hi; const bf16x8 vf = *(const bf16x8*)vb;
;             O0[eb] = MFMA32(vf, p0[kk], O0[eb]); O1[eb] = MFMA32(vf, p1[kk], O1[eb]); } }
	v_mfma_f32_32x32x16_bf16 v[96:111], v[166:169], v[112:115], v[48:63]
	v_exp_f32_e32 v116, v116
	v_exp_f32_e32 v117, v117
	v_exp_f32_e32 v118, v118
	v_exp_f32_e32 v119, v119
	v_mfma_f32_32x32x16_bf16 v[96:111], v[170:173], v[42:45], v[96:111]
	v_exp_f32_e32 v120, v120
	v_exp_f32_e32 v121, v121
	v_exp_f32_e32 v122, v122
	v_exp_f32_e32 v123, v123
	ds_read_b128 v[166:169], v148 offset:36864
	ds_read_b128 v[170:173], v149 offset:36864
	v_mfma_f32_32x32x16_bf16 v[64:79], v[174:177], v[158:161], v[64:79]
	v_exp_f32_e32 v124, v124
	v_exp_f32_e32 v125, v125
	v_add_f32_e32 v140, v140, v116
	v_add_f32_e32 v151, v151, v117
	v_add_f32_e32 v140, v140, v118
	v_add_f32_e32 v151, v151, v119
	v_mfma_f32_32x32x16_bf16 v[0:15], v[182:185], v[158:161], v[0:15]
	v_exp_f32_e32 v126, v126
	v_exp_f32_e32 v127, v127
	v_cvt_pk_bf16_f32 v158, v116, v117
	v_cvt_pk_bf16_f32 v159, v118, v119
	v_add_f32_e32 v140, v140, v120
	v_add_f32_e32 v151, v151, v121
	v_mfma_f32_32x32x16_bf16 v[64:79], v[178:181], v[162:165], v[64:79]
	v_exp_f32_e32 v128, v128
	v_exp_f32_e32 v129, v129
	v_cvt_pk_bf16_f32 v160, v120, v121
	v_cvt_pk_bf16_f32 v161, v122, v123
	v_add_f32_e32 v140, v140, v122
	v_add_f32_e32 v151, v151, v123
	v_mfma_f32_32x32x16_bf16 v[0:15], v[186:189], v[162:165], v[0:15]
	v_exp_f32_e32 v130, v130
	v_exp_f32_e32 v131, v131
	v_add_f32_e32 v140, v140, v124
	v_add_f32_e32 v151, v151, v125
	v_add_f32_e32 v140, v140, v126
	v_add_f32_e32 v151, v151, v127
	v_add_f32_e32 v140, v140, v128
	v_add_f32_e32 v151, v151, v129
	v_cvt_pk_bf16_f32 v162, v124, v125
	v_cvt_pk_bf16_f32 v163, v126, v127
	v_cvt_pk_bf16_f32 v164, v128, v129
	v_add_f32_e32 v140, v140, v130
	v_add_f32_e32 v151, v151, v131
	v_cvt_pk_bf16_f32 v165, v130, v131
	s_waitcnt lgkmcnt(0)
	v_mfma_f32_32x32x16_bf16 v[116:131], v[166:169], v[38:41], v[48:63]
	v_exp_f32_e32 v96, v96
	v_exp_f32_e32 v97, v97
	v_exp_f32_e32 v98, v98
	v_exp_f32_e32 v99, v99
	v_mfma_f32_32x32x16_bf16 v[116:131], v[170:173], v[34:37], v[116:131]
	v_exp_f32_e32 v100, v100
	v_exp_f32_e32 v101, v101
	v_exp_f32_e32 v102, v102
	v_exp_f32_e32 v103, v103
	ds_read_b128 v[166:169], v146
	ds_read_b128 v[170:173], v147
	v_mfma_f32_32x32x16_bf16 v[80:95], v[174:177], v[158:161], v[80:95]
	v_exp_f32_e32 v104, v104
	v_exp_f32_e32 v105, v105
	v_add_f32_e32 v141, v141, v96
	v_add_f32_e32 v150, v150, v97
	v_add_f32_e32 v141, v141, v98
	v_add_f32_e32 v150, v150, v99
	v_mfma_f32_32x32x16_bf16 v[16:31], v[182:185], v[158:161], v[16:31]
	v_exp_f32_e32 v106, v106
	v_exp_f32_e32 v107, v107
	v_cvt_pk_bf16_f32 v158, v96, v97
	v_cvt_pk_bf16_f32 v159, v98, v99
	v_add_f32_e32 v141, v141, v100
	v_add_f32_e32 v150, v150, v101
	v_mfma_f32_32x32x16_bf16 v[80:95], v[178:181], v[162:165], v[80:95]
	v_exp_f32_e32 v108, v108
	v_exp_f32_e32 v109, v109
	v_cvt_pk_bf16_f32 v160, v100, v101
	v_cvt_pk_bf16_f32 v161, v102, v103
	v_add_f32_e32 v141, v141, v102
	v_add_f32_e32 v150, v150, v103
	v_mfma_f32_32x32x16_bf16 v[16:31], v[186:189], v[162:165], v[16:31]
	ds_read_b128 v[174:177], v148 offset:40960
	ds_read_b128 v[178:181], v149 offset:40960
	ds_read_b128 v[182:185], v148 offset:45056
	ds_read_b128 v[186:189], v149 offset:45056
	v_exp_f32_e32 v110, v110
	v_exp_f32_e32 v111, v111
	v_add_f32_e32 v141, v141, v104
	v_add_f32_e32 v150, v150, v105
	v_add_f32_e32 v141, v141, v106
	v_add_f32_e32 v150, v150, v107
	v_add_f32_e32 v141, v141, v108
	v_add_f32_e32 v150, v150, v109
	v_cvt_pk_bf16_f32 v162, v104, v105
	v_cvt_pk_bf16_f32 v163, v106, v107
	v_cvt_pk_bf16_f32 v164, v108, v109
	v_add_f32_e32 v141, v141, v110
	v_add_f32_e32 v150, v150, v111
	v_cvt_pk_bf16_f32 v165, v110, v111
	s_waitcnt lgkmcnt(0)
	v_mfma_f32_32x32x16_bf16 v[96:111], v[166:169], v[112:115], v[48:63]
	v_exp_f32_e32 v116, v116
	v_exp_f32_e32 v117, v117
	v_exp_f32_e32 v118, v118
	v_exp_f32_e32 v119, v119
	v_mfma_f32_32x32x16_bf16 v[96:111], v[170:173], v[42:45], v[96:111]
	v_exp_f32_e32 v120, v120
	v_exp_f32_e32 v121, v121
	v_exp_f32_e32 v122, v122
	v_exp_f32_e32 v123, v123
	ds_read_b128 v[166:169], v148
	ds_read_b128 v[170:173], v149
	v_mfma_f32_32x32x16_bf16 v[64:79], v[174:177], v[158:161], v[64:79]
	v_exp_f32_e32 v124, v124
	v_exp_f32_e32 v125, v125
	v_add_f32_e32 v140, v140, v116
	v_add_f32_e32 v151, v151, v117
	v_add_f32_e32 v140, v140, v118
	v_add_f32_e32 v151, v151, v119
	v_mfma_f32_32x32x16_bf16 v[0:15], v[182:185], v[158:161], v[0:15]
	v_exp_f32_e32 v126, v126
	v_exp_f32_e32 v127, v127
	v_cvt_pk_bf16_f32 v158, v116, v117
	v_cvt_pk_bf16_f32 v159, v118, v119
	v_add_f32_e32 v140, v140, v120
	v_add_f32_e32 v151, v151, v121
	v_mfma_f32_32x32x16_bf16 v[64:79], v[178:181], v[162:165], v[64:79]
	v_exp_f32_e32 v128, v128
	v_exp_f32_e32 v129, v129
	v_cvt_pk_bf16_f32 v160, v120, v121
	v_cvt_pk_bf16_f32 v161, v122, v123
	v_add_f32_e32 v140, v140, v122
	v_add_f32_e32 v151, v151, v123
	v_mfma_f32_32x32x16_bf16 v[0:15], v[186:189], v[162:165], v[0:15]
	v_exp_f32_e32 v130, v130
	v_exp_f32_e32 v131, v131
	v_add_f32_e32 v140, v140, v124
	v_add_f32_e32 v151, v151, v125
	v_add_f32_e32 v140, v140, v126
	v_add_f32_e32 v151, v151, v127
	v_add_f32_e32 v140, v140, v128
	v_add_f32_e32 v151, v151, v129
	v_cvt_pk_bf16_f32 v162, v124, v125
	v_cvt_pk_bf16_f32 v163, v126, v127
	v_cvt_pk_bf16_f32 v164, v128, v129
	v_add_f32_e32 v140, v140, v130
	v_add_f32_e32 v151, v151, v131
	v_cvt_pk_bf16_f32 v165, v130, v131
	s_add_i32 s4, s4, 1
	s_waitcnt vmcnt(0) lgkmcnt(0)
	s_barrier
	s_cmp_le_u32 s4, s5
	s_cbranch_scc1 .Lc_tile_ph0
	s_mov_b32 s9, 0

; template <int MODE>
; DI void attn_unit(unsigned char* lds, const AttnParams& ap, int b, int h, int qb, int tid) {
;     ...
;   for (int n = 0; n < ntiles; n += NCH) {
;     const int jb = (MODE == 2) ? jhi - n : jlo + n;
;     __syncthreads();
;     if (MODE == 2 && D_EARLY) { int alld = 1;
; #pragma unroll
;       for (int w = 0; w < 8; ++w) alld &= flags[w];
;       if (alld) break; }
; #pragma unroll
;     for (int c = 0; c < NCH; ++c) { *(u32x4*)(Ks0 + (c * 64 + lrow) * 72 + 8 * lch) = kreg[c]; *(u32x4*)(Vs0 + (c * 64 + lrow) * 72 + 8 * lch) = vreg[c]; }
;     __syncthreads();
;     if (n + NCH < ntiles) {
; #pragma unroll
;       for (int c = 0; c < NCH; ++c) { const int jn = (MODE == 2) ? jb - NCH - c : jb + NCH + c; kreg[c] = *(const u32x4*)(kg + (size_t)jn * 64 * PLD); vreg[c] = *(const u32x4*)(vg + (size_t)jn * 4096); } }
;     ...
;     const bool active = (j <= cw) && (MODE != 0 || j >= cw - 8);
;     if (!active) continue;
.Lc_idle_ph0:
	s_add_i32 m0, s0, 32768
	s_nop 0
	global_load_lds_dwordx4 v32, s[2:3]
	s_add_i32 m0, s0, 40960
	s_nop 0
	global_load_lds_dwordx4 v157, s[10:11]
	s_add_u32 s2, s2, 0x68800
	s_addc_u32 s3, s3, 0
	s_add_u32 s10, s10, 0x2000
	s_addc_u32 s11, s11, 0
	s_add_i32 s4, s4, 1
	s_waitcnt vmcnt(0) lgkmcnt(0)
	s_barrier
	s_cmp_gt_u32 s4, s8
	s_cbranch_scc1 .Lc_tiles_done
.Lc_idle_ph1:
	s_add_i32 m0, s0, 0
	s_nop 0
	global_load_lds_dwordx4 v32, s[2:3]
	s_add_i32 m0, s0, 8192
	s_nop 0
	global_load_lds_dwordx4 v157, s[10:11]
	s_add_u32 s2, s2, 0x68800
	s_addc_u32 s3, s3, 0
	s_add_u32 s10, s10, 0x2000
	s_addc_u32 s11, s11, 0
	s_add_i32 s4, s4, 1
	s_waitcnt vmcnt(0) lgkmcnt(0)
	s_barrier
	s_cmp_gt_u32 s4, s8
	s_cbranch_scc1 .Lc_tiles_done
.Lc_idle_ph2:
	s_add_i32 m0, s0, 16384
	s_nop 0
	global_load_lds_dwordx4 v32, s[2:3]
	s_add_i32 m0, s0, 24576
	s_nop 0
	global_load_lds_dwordx4 v157, s[10:11]
	s_add_u32 s2, s2, 0x68800
	s_addc_u32 s3, s3, 0
	s_add_u32 s10, s10, 0x2000
	s_addc_u32 s11, s11, 0
	s_add_i32 s4, s4, 1
	s_waitcnt vmcnt(0) lgkmcnt(0)
	s_barrier
	s_cmp_gt_u32 s4, s8
	s_cbranch_scc1 .Lc_tiles_done
	s_branch .Lc_idle_ph0
